# attention importance table: XOR-swizzled columns so the tap writes are bank-conflict free; on top of v38
# speedup vs baseline: 1.0084x; 1.0084x over previous
.LBB0_1697:
	s_or_b64 exec, exec, s[4:5]
	v_max_f32_e64 v0, |v125|, |v125|
	v_max_f32_e64 v99, |v124|, |v124|
	v_max_f32_e32 v0, v99, v0
	ds_swizzle_b32 v99, v0 offset:swizzle(SWAP,1)
	v_max3_f32 v107, v119, v120, v121
	ds_swizzle_b32 v108, v107 offset:swizzle(SWAP,1)
	v_lshlrev_b32_e32 v103, 1, v155
	v_lshlrev_b32_e32 v102, 4, v155
	s_waitcnt lgkmcnt(1)
	v_max_f32_e32 v99, v99, v99
	v_max_f32_e32 v0, v0, v99
	ds_swizzle_b32 v99, v0 offset:swizzle(SWAP,2)
	s_waitcnt lgkmcnt(1)
	v_max_f32_e32 v108, v108, v108
	v_max_f32_e32 v107, v107, v108
	ds_swizzle_b32 v108, v107 offset:swizzle(SWAP,2)
	v_and_b32_e32 v104, 0x100, v151
	s_waitcnt lgkmcnt(1)
	v_max_f32_e32 v99, v99, v99
	v_max_f32_e32 v0, v0, v99
	ds_swizzle_b32 v99, v0 offset:swizzle(SWAP,4)
	v_and_b32_e32 v103, 32, v103
	v_and_b32_e32 v102, 0xc0, v102
	v_add3_u32 v103, v104, 0, v103
	v_add3_u32 v181, v103, v102, v98
	s_waitcnt lgkmcnt(1)
	v_max_f32_e32 v98, v108, v108
	v_max_f32_e64 v103, |v112|, |v112|
	v_max_f32_e64 v104, |v111|, |v111|
	v_max_f32_e32 v98, v107, v98
	v_max_f32_e32 v103, v104, v103
	s_waitcnt lgkmcnt(0)
	v_max_f32_e32 v99, v99, v99
	ds_swizzle_b32 v102, v98 offset:swizzle(SWAP,4)
	ds_swizzle_b32 v104, v103 offset:swizzle(SWAP,1)
	v_max_f32_e32 v0, v0, v99
	ds_swizzle_b32 v99, v0 offset:swizzle(SWAP,8)
	v_max_f32_e64 v101, |v101|, |v101|
	s_waitcnt lgkmcnt(2)
	v_max_f32_e32 v102, v102, v102
	s_waitcnt lgkmcnt(1)
	v_max_f32_e32 v104, v104, v104
	v_max_f32_e32 v98, v98, v102
	v_max_f32_e32 v103, v103, v104
	s_waitcnt lgkmcnt(0)
	v_max_f32_e32 v99, v99, v99
	ds_swizzle_b32 v102, v98 offset:swizzle(SWAP,8)
	ds_swizzle_b32 v104, v103 offset:swizzle(SWAP,2)
	v_max_f32_e32 v0, v0, v99
	ds_swizzle_b32 v99, v0 offset:swizzle(SWAP,16)
	v_max_f32_e64 v100, |v100|, |v100|
	s_waitcnt lgkmcnt(2)
	v_max_f32_e32 v102, v102, v102
	s_waitcnt lgkmcnt(1)
	v_max_f32_e32 v104, v104, v104
	v_max_f32_e32 v98, v98, v102
	v_max_f32_e32 v103, v103, v104
	s_waitcnt lgkmcnt(0)
	v_max_f32_e32 v99, v99, v99
	ds_swizzle_b32 v102, v98 offset:swizzle(SWAP,16)
	ds_swizzle_b32 v104, v103 offset:swizzle(SWAP,4)
	v_max_f32_e32 v0, v0, v99
	v_mov_b32_e32 v99, v0
	s_nop 1
	v_permlane32_swap_b32_e32 v0, v99
	v_max_f32_e32 v99, v99, v99
	v_max_f32_e32 v0, v0, v0
	v_max_f32_e32 v0, v0, v99
	s_waitcnt lgkmcnt(1)
	v_max_f32_e32 v99, v102, v102
	s_waitcnt lgkmcnt(0)
	v_max_f32_e32 v102, v104, v104
	v_max_f32_e32 v102, v103, v102
	ds_swizzle_b32 v103, v102 offset:swizzle(SWAP,8)
	v_max_f32_e32 v98, v98, v99
	v_mov_b32_e32 v99, v98
	s_nop 1
	v_permlane32_swap_b32_e32 v98, v99
	v_max_f32_e32 v99, v99, v99
	v_max_f32_e32 v98, v98, v98
	v_max_f32_e32 v190, v98, v99
	s_waitcnt lgkmcnt(0)
	v_max_f32_e32 v98, v103, v103
	v_max_f32_e32 v98, v102, v98
	v_max_f32_e64 v102, |v106|, |v106|
	v_max_f32_e64 v103, |v105|, |v105|
	v_max_f32_e32 v102, v103, v102
	ds_swizzle_b32 v99, v98 offset:swizzle(SWAP,16)
	ds_swizzle_b32 v103, v102 offset:swizzle(SWAP,1)
	v_max_f32_e32 v100, v100, v101
	ds_swizzle_b32 v101, v100 offset:swizzle(SWAP,1)
	v_mul_f32_e32 v191, 0x4182b55c, v0
	s_waitcnt lgkmcnt(2)
	v_max_f32_e32 v0, v99, v99
	s_waitcnt lgkmcnt(1)
	v_max_f32_e32 v99, v103, v103
	v_max_f32_e32 v99, v102, v99
	s_waitcnt lgkmcnt(0)
	v_max_f32_e32 v101, v101, v101
	ds_swizzle_b32 v102, v99 offset:swizzle(SWAP,2)
	v_max_f32_e32 v100, v100, v101
	ds_swizzle_b32 v101, v100 offset:swizzle(SWAP,2)
	v_max_f32_e32 v0, v98, v0
	v_mov_b32_e32 v98, v0
	s_waitcnt lgkmcnt(1)
	v_max_f32_e32 v102, v102, v102
	v_max_f32_e32 v99, v99, v102
	s_waitcnt lgkmcnt(0)
	v_max_f32_e32 v101, v101, v101
	ds_swizzle_b32 v102, v99 offset:swizzle(SWAP,4)
	v_max_f32_e32 v100, v100, v101
	ds_swizzle_b32 v101, v100 offset:swizzle(SWAP,4)
	v_permlane32_swap_b32_e32 v0, v98
	s_waitcnt lgkmcnt(1)
	v_max_f32_e32 v102, v102, v102
	v_max_f32_e32 v99, v99, v102
	s_waitcnt lgkmcnt(0)
	v_max_f32_e32 v101, v101, v101
	ds_swizzle_b32 v102, v99 offset:swizzle(SWAP,8)
	v_max_f32_e32 v100, v100, v101
	ds_swizzle_b32 v101, v100 offset:swizzle(SWAP,8)
	v_max_f32_e32 v98, v98, v98
	v_max_f32_e32 v0, v0, v0
	s_waitcnt lgkmcnt(1)
	v_max_f32_e32 v102, v102, v102
	v_max_f32_e32 v99, v99, v102
	v_max_f32_e32 v0, v0, v98
	s_waitcnt lgkmcnt(0)
	v_max_f32_e32 v98, v101, v101
	ds_swizzle_b32 v102, v99 offset:swizzle(SWAP,16)
	v_max_f32_e32 v98, v100, v98
	ds_swizzle_b32 v100, v98 offset:swizzle(SWAP,16)
	v_fma_f32 v0, v191, v0, v190
	v_add_f32_e32 v195, 0x3d4ccccd, v0
	s_waitcnt lgkmcnt(1)
	v_max_f32_e32 v0, v102, v102
	v_max_f32_e32 v0, v99, v0
	s_waitcnt lgkmcnt(0)
	v_max_f32_e32 v99, v100, v100
	v_max_f32_e32 v192, v98, v99
	v_lshlrev_b32_e32 v98, 16, v94
	v_and_b32_e32 v94, 0xffff0000, v94
	v_mul_f32_e32 v102, v94, v94
	v_lshlrev_b32_e32 v99, 16, v95
	v_fmac_f32_e32 v102, v98, v98
	v_and_b32_e32 v95, 0xffff0000, v95
	v_fmac_f32_e32 v102, v99, v99
	v_lshlrev_b32_e32 v100, 16, v96
	v_fmac_f32_e32 v102, v95, v95
	v_and_b32_e32 v96, 0xffff0000, v96
	v_fmac_f32_e32 v102, v100, v100
	v_lshlrev_b32_e32 v101, 16, v97
	v_fmac_f32_e32 v102, v96, v96
	v_and_b32_e32 v97, 0xffff0000, v97
	v_fmac_f32_e32 v102, v101, v101
	v_fmac_f32_e32 v102, v97, v97
	v_lshlrev_b32_e32 v103, 16, v90
	v_and_b32_e32 v90, 0xffff0000, v90
	v_fmac_f32_e32 v102, v103, v103
	v_lshlrev_b32_e32 v104, 16, v91
	v_fmac_f32_e32 v102, v90, v90
	v_and_b32_e32 v91, 0xffff0000, v91
	v_fmac_f32_e32 v102, v104, v104
	v_lshlrev_b32_e32 v105, 16, v92
	v_fmac_f32_e32 v102, v91, v91
	v_and_b32_e32 v92, 0xffff0000, v92
	v_fmac_f32_e32 v102, v105, v105
	v_lshlrev_b32_e32 v106, 16, v93
	v_fmac_f32_e32 v102, v92, v92
	v_and_b32_e32 v93, 0xffff0000, v93
	v_fmac_f32_e32 v102, v106, v106
	v_fmac_f32_e32 v102, v93, v93
	v_lshlrev_b32_e32 v107, 16, v86
	v_and_b32_e32 v86, 0xffff0000, v86
	v_fmac_f32_e32 v102, v107, v107
	v_lshlrev_b32_e32 v108, 16, v87
	v_fmac_f32_e32 v102, v86, v86
	v_and_b32_e32 v87, 0xffff0000, v87
	v_fmac_f32_e32 v102, v108, v108
	v_lshlrev_b32_e32 v109, 16, v88
	v_fmac_f32_e32 v102, v87, v87
	v_and_b32_e32 v88, 0xffff0000, v88
	v_fmac_f32_e32 v102, v109, v109
	v_lshlrev_b32_e32 v110, 16, v89
	v_fmac_f32_e32 v102, v88, v88
	v_and_b32_e32 v89, 0xffff0000, v89
	v_fmac_f32_e32 v102, v110, v110
	v_fmac_f32_e32 v102, v89, v89
	v_lshlrev_b32_e32 v111, 16, v82
	v_and_b32_e32 v82, 0xffff0000, v82
	v_fmac_f32_e32 v102, v111, v111
	v_lshlrev_b32_e32 v112, 16, v83
	v_fmac_f32_e32 v102, v82, v82
	v_and_b32_e32 v83, 0xffff0000, v83
	v_fmac_f32_e32 v102, v112, v112
	v_lshlrev_b32_e32 v113, 16, v84
	v_fmac_f32_e32 v102, v83, v83
	v_and_b32_e32 v84, 0xffff0000, v84
	v_fmac_f32_e32 v102, v113, v113
	v_lshlrev_b32_e32 v114, 16, v85
	v_fmac_f32_e32 v102, v84, v84
	v_and_b32_e32 v85, 0xffff0000, v85
	v_fmac_f32_e32 v102, v114, v114
	v_fmac_f32_e32 v102, v85, v85
	v_lshlrev_b32_e32 v115, 16, v78
	v_and_b32_e32 v78, 0xffff0000, v78
	v_fmac_f32_e32 v102, v115, v115
	v_lshlrev_b32_e32 v116, 16, v79
	v_fmac_f32_e32 v102, v78, v78
	v_and_b32_e32 v79, 0xffff0000, v79
	v_fmac_f32_e32 v102, v116, v116
	v_lshlrev_b32_e32 v117, 16, v80
	v_fmac_f32_e32 v102, v79, v79
	v_and_b32_e32 v80, 0xffff0000, v80
	v_fmac_f32_e32 v102, v117, v117
	v_lshlrev_b32_e32 v118, 16, v81
	v_fmac_f32_e32 v102, v80, v80
	v_and_b32_e32 v81, 0xffff0000, v81
	v_fmac_f32_e32 v102, v118, v118
	v_fmac_f32_e32 v102, v81, v81
	v_lshlrev_b32_e32 v119, 16, v74
	v_and_b32_e32 v74, 0xffff0000, v74
	v_fmac_f32_e32 v102, v119, v119
	v_lshlrev_b32_e32 v120, 16, v75
	v_fmac_f32_e32 v102, v74, v74
	v_and_b32_e32 v75, 0xffff0000, v75
	v_fmac_f32_e32 v102, v120, v120
	v_lshlrev_b32_e32 v121, 16, v76
	v_fmac_f32_e32 v102, v75, v75
	v_and_b32_e32 v76, 0xffff0000, v76
	v_fmac_f32_e32 v102, v121, v121
	v_lshlrev_b32_e32 v122, 16, v77
	v_fmac_f32_e32 v102, v76, v76
	v_and_b32_e32 v77, 0xffff0000, v77
	v_fmac_f32_e32 v102, v122, v122
	v_fmac_f32_e32 v102, v77, v77
	v_lshlrev_b32_e32 v123, 16, v70
	v_and_b32_e32 v70, 0xffff0000, v70
	v_fmac_f32_e32 v102, v123, v123
	v_lshlrev_b32_e32 v124, 16, v71
	v_fmac_f32_e32 v102, v70, v70
	v_and_b32_e32 v71, 0xffff0000, v71
	v_fmac_f32_e32 v102, v124, v124
	v_lshlrev_b32_e32 v125, 16, v72
	v_fmac_f32_e32 v102, v71, v71
	v_and_b32_e32 v72, 0xffff0000, v72
	v_fmac_f32_e32 v102, v125, v125
	v_lshlrev_b32_e32 v126, 16, v73
	v_fmac_f32_e32 v102, v72, v72
	v_and_b32_e32 v73, 0xffff0000, v73
	v_fmac_f32_e32 v102, v126, v126
	v_fmac_f32_e32 v102, v73, v73
	v_lshlrev_b32_e32 v127, 16, v66
	v_and_b32_e32 v66, 0xffff0000, v66
	v_fmac_f32_e32 v102, v127, v127
	v_lshlrev_b32_e32 v159, 16, v67
	v_fmac_f32_e32 v102, v66, v66
	v_and_b32_e32 v67, 0xffff0000, v67
	v_fmac_f32_e32 v102, v159, v159
	v_lshlrev_b32_e32 v164, 16, v68
	v_fmac_f32_e32 v102, v67, v67
	v_and_b32_e32 v68, 0xffff0000, v68
	v_fmac_f32_e32 v102, v164, v164
	v_lshlrev_b32_e32 v165, 16, v69
	v_fmac_f32_e32 v102, v68, v68
	v_and_b32_e32 v69, 0xffff0000, v69
	v_fmac_f32_e32 v102, v165, v165
	v_fmac_f32_e32 v102, v69, v69
	v_mov_b32_e32 v166, v102
	s_nop 1
	v_permlane32_swap_b32_e32 v102, v166
	v_add_f32_e32 v102, v102, v166
	v_fmamk_f32 v102, v102, 0x3c000000, v163
	v_rsq_f32_e32 v102, v102
	s_cmpk_gt_u32 s55, 0x1ff
	s_cselect_b64 s[8:9], -1, 0
	s_cmpk_lt_u32 s55, 0x200
	v_mul_f32_e32 v102, 0x3db504f3, v102
	v_mul_f32_e32 v166, 0x3fb8aa3b, v102
	v_mul_f32_e32 v94, v166, v94
	v_mul_f32_e32 v63, v63, v94
	v_mul_f32_e32 v94, v166, v96
	v_mul_f32_e32 v98, v166, v98
	v_mul_f32_e32 v59, v59, v94
	v_mul_f32_e32 v94, v166, v99
	v_mul_f32_e32 v62, v62, v98
	v_mul_f32_e32 v98, v166, v100
	v_mul_f32_e32 v64, v64, v94
	v_mul_f32_e32 v94, v166, v101
	v_mul_f32_e32 v58, v58, v98
	v_mul_f32_e32 v60, v60, v94
	v_mul_f32_e32 v94, v166, v95
	v_mul_f32_e32 v65, v65, v94
	v_cvt_pk_bf16_f32 v98, v62, v63
	v_cvt_pk_bf16_f32 v99, v64, v65
	v_cvt_pk_bf16_f32 v100, v58, v59
	v_mul_f32_e32 v58, v166, v103
	v_mul_f32_e32 v54, v54, v58
	v_mul_f32_e32 v58, v166, v105
	v_mul_f32_e32 v50, v50, v58
	v_mul_f32_e32 v58, v166, v90
	v_mul_f32_e32 v55, v55, v58
	v_mul_f32_e32 v58, v166, v92
	v_mul_f32_e32 v51, v51, v58
	v_mul_f32_e32 v58, v166, v104
	v_mul_f32_e32 v56, v56, v58
	v_mul_f32_e32 v58, v166, v106
	v_mul_f32_e32 v94, v166, v97
	v_mul_f32_e32 v52, v52, v58
	v_mul_f32_e32 v58, v166, v91
	v_mul_f32_e32 v61, v61, v94
	v_cvt_pk_bf16_f32 v101, v60, v61
	v_mul_f32_e32 v57, v57, v58
	v_cvt_pk_bf16_f32 v102, v54, v55
	v_cvt_pk_bf16_f32 v103, v56, v57
	v_cvt_pk_bf16_f32 v104, v50, v51
	v_mul_f32_e32 v50, v166, v107
	v_mul_f32_e32 v46, v46, v50
	v_mul_f32_e32 v50, v166, v109
	v_mul_f32_e32 v42, v42, v50
	v_mul_f32_e32 v50, v166, v86
	v_mul_f32_e32 v47, v47, v50
	v_mul_f32_e32 v50, v166, v88
	v_mul_f32_e32 v43, v43, v50
	v_mul_f32_e32 v50, v166, v108
	v_mul_f32_e32 v48, v48, v50
	v_mul_f32_e32 v50, v166, v110
	v_mul_f32_e32 v58, v166, v93
	v_mul_f32_e32 v44, v44, v50
	v_mul_f32_e32 v50, v166, v87
	v_mul_f32_e32 v53, v53, v58
	v_cvt_pk_bf16_f32 v105, v52, v53
	v_mul_f32_e32 v49, v49, v50
	v_cvt_pk_bf16_f32 v106, v46, v47
	v_cvt_pk_bf16_f32 v107, v48, v49
	v_cvt_pk_bf16_f32 v108, v42, v43
	v_mul_f32_e32 v42, v166, v111
	v_mul_f32_e32 v38, v38, v42
	v_mul_f32_e32 v42, v166, v113
	v_mul_f32_e32 v34, v34, v42
	v_mul_f32_e32 v42, v166, v82
	v_mul_f32_e32 v39, v39, v42
	v_mul_f32_e32 v42, v166, v84
	v_mul_f32_e32 v35, v35, v42
	v_mul_f32_e32 v42, v166, v112
	v_mul_f32_e32 v40, v40, v42
	v_mul_f32_e32 v42, v166, v114
	v_mul_f32_e32 v50, v166, v89
	v_mul_f32_e32 v36, v36, v42
	v_mul_f32_e32 v42, v166, v83
	v_mul_f32_e32 v45, v45, v50
	v_cvt_pk_bf16_f32 v109, v44, v45
	v_mul_f32_e32 v41, v41, v42
	v_cvt_pk_bf16_f32 v110, v38, v39
	v_cvt_pk_bf16_f32 v111, v40, v41
	v_cvt_pk_bf16_f32 v112, v34, v35
	v_mul_f32_e32 v34, v166, v115
	v_mul_f32_e32 v30, v30, v34
	v_mul_f32_e32 v34, v166, v117
	v_mul_f32_e32 v26, v26, v34
	v_mul_f32_e32 v34, v166, v78
	v_mul_f32_e32 v31, v31, v34
	v_mul_f32_e32 v34, v166, v80
	v_mul_f32_e32 v27, v27, v34
	v_mul_f32_e32 v34, v166, v116
	v_mul_f32_e32 v32, v32, v34
	v_mul_f32_e32 v34, v166, v118
	v_mul_f32_e32 v42, v166, v85
	v_mul_f32_e32 v28, v28, v34
	v_mul_f32_e32 v34, v166, v79
	v_mul_f32_e32 v37, v37, v42
	v_cvt_pk_bf16_f32 v113, v36, v37
	v_mul_f32_e32 v33, v33, v34
	v_cvt_pk_bf16_f32 v114, v30, v31
	v_cvt_pk_bf16_f32 v115, v32, v33
	v_cvt_pk_bf16_f32 v116, v26, v27
	v_mul_f32_e32 v26, v166, v119
	v_mul_f32_e32 v22, v22, v26
	v_mul_f32_e32 v26, v166, v121
	v_mul_f32_e32 v18, v18, v26
	v_mul_f32_e32 v26, v166, v74
	v_mul_f32_e32 v23, v23, v26
	v_mul_f32_e32 v26, v166, v76
	v_mul_f32_e32 v19, v19, v26
	v_mul_f32_e32 v26, v166, v120
	v_mul_f32_e32 v24, v24, v26
	v_mul_f32_e32 v26, v166, v122
	v_mul_f32_e32 v34, v166, v81
	v_mul_f32_e32 v20, v20, v26
	v_mul_f32_e32 v26, v166, v75
	v_mul_f32_e32 v29, v29, v34
	v_cvt_pk_bf16_f32 v117, v28, v29
	v_mul_f32_e32 v25, v25, v26
	v_cvt_pk_bf16_f32 v118, v22, v23
	v_cvt_pk_bf16_f32 v119, v24, v25
	v_cvt_pk_bf16_f32 v120, v18, v19
	v_mul_f32_e32 v18, v166, v123
	v_mul_f32_e32 v14, v14, v18
	v_mul_f32_e32 v18, v166, v125
	v_mul_f32_e32 v10, v10, v18
	v_mul_f32_e32 v18, v166, v70
	v_mul_f32_e32 v15, v15, v18
	v_mul_f32_e32 v18, v166, v72
	v_mul_f32_e32 v11, v11, v18
	v_mul_f32_e32 v18, v166, v124
	v_mul_f32_e32 v16, v16, v18
	v_mul_f32_e32 v18, v166, v126
	v_mul_f32_e32 v26, v166, v77
	v_mul_f32_e32 v12, v12, v18
	v_mul_f32_e32 v18, v166, v71
	v_mul_f32_e32 v21, v21, v26
	v_cvt_pk_bf16_f32 v121, v20, v21
	v_mul_f32_e32 v17, v17, v18
	v_cvt_pk_bf16_f32 v122, v14, v15
	v_cvt_pk_bf16_f32 v123, v16, v17
	v_cvt_pk_bf16_f32 v124, v10, v11
	v_mul_f32_e32 v10, v166, v127
	v_mul_f32_e32 v6, v6, v10
	v_mul_f32_e32 v10, v166, v164
	v_mul_f32_e32 v2, v2, v10
	v_mul_f32_e32 v10, v166, v66
	v_mul_f32_e32 v7, v7, v10
	v_mul_f32_e32 v10, v166, v68
	v_mul_f32_e32 v3, v3, v10
	v_mul_f32_e32 v10, v166, v159
	v_mul_f32_e32 v18, v166, v73
	v_mul_f32_e32 v8, v8, v10
	v_mul_f32_e32 v10, v166, v165
	v_add_f32_e32 v11, 0, v132
	v_mul_f32_e32 v13, v13, v18
	v_cvt_pk_bf16_f32 v125, v12, v13
	v_mul_f32_e32 v4, v4, v10
	v_mul_f32_e32 v10, v166, v67
	v_add_f32_e32 v11, v11, v136
	v_cvt_pk_bf16_f32 v126, v6, v7
	v_add_f32_e32 v7, 0, v133
	v_mul_f32_e32 v9, v9, v10
	v_add_f32_e32 v11, v11, v140
	v_cvt_pk_bf16_f32 v127, v8, v9
	v_add_f32_e32 v7, v7, v137
	v_add_f32_e32 v8, 0, v134
	v_add_f32_e32 v11, v11, v144
	v_add_f32_e32 v7, v7, v141
	v_add_f32_e32 v8, v8, v138
	v_add_f32_e32 v11, v11, v148
	v_add_f32_e32 v7, v7, v145
	v_add_f32_e32 v8, v8, v142
	v_add_f32_e32 v11, v11, v152
	v_add_f32_e32 v7, v7, v149
	v_add_f32_e32 v8, v8, v146
	v_add_f32_e32 v11, v11, v156
	v_add_f32_e32 v7, v7, v153
	v_add_f32_e32 v8, v8, v150
	v_add_f32_e32 v11, v11, v160
	v_add_f32_e32 v7, v7, v157
	v_add_f32_e32 v8, v8, v154
	v_fma_f32 v11, v131, v11, v128
	v_add_f32_e32 v7, v7, v161
	v_add_f32_e32 v8, v8, v158
	v_mul_f32_e32 v11, 0xbfb8aa3b, v11
	v_fma_f32 v7, v131, v7, v129
	v_add_f32_e32 v8, v8, v162
	v_exp_f32_e32 v11, v11
	v_mul_f32_e32 v7, 0xbfb8aa3b, v7
	v_fmac_f32_e32 v130, v131, v8
	v_exp_f32_e32 v7, v7
	v_mul_f32_e32 v8, 0xbfb8aa3b, v130
	v_exp_f32_e32 v8, v8
	s_cselect_b32 s10, 3, 1
	s_lshl_b32 s58, s20, 18
	s_lshl_b32 s4, s20, 19
	v_readlane_b32 s5, v254, 51
	s_add_u32 s14, s5, s4
	v_readlane_b32 s5, v254, 52
	v_add_f32_e32 v6, 1.0, v11
	s_addc_u32 s15, s5, 0
	v_readlane_b32 s5, v254, 53
	v_rcp_f32_e32 v134, v6
	v_add_f32_e32 v6, 1.0, v7
	s_add_u32 s16, s5, s4
	v_readlane_b32 s4, v254, 54
	v_rcp_f32_e32 v145, v6
	v_add_f32_e32 v6, 1.0, v8
	s_addc_u32 s17, s4, 0
	s_mul_i32 s4, s3, 0x210
	v_mul_f32_e32 v10, v166, v69
	v_rcp_f32_e32 v136, v6
	v_cvt_pk_bf16_f32 v128, v2, v3
	s_add_i32 s52, s4, 0
	v_lshlrev_b32_e32 v2, 4, v143
	s_movk_i32 s4, 0x70
	v_mul_f32_e32 v5, v5, v10
	v_cvt_pk_bf16_f32 v129, v4, v5
	s_waitcnt vmcnt(0) lgkmcnt(0)
	v_and_b32_e32 v3, 0x70, v2
	v_bitop3_b32 v138, v180, v2, s4 bitop3:0x78
	s_movk_i32 s4, 0x60
	s_lshl_b32 s12, s3, 12
	v_lshlrev_b32_e32 v2, 7, v143
	s_add_i32 s13, 0, 0x1c000
	v_lshlrev_b32_e32 v144, 2, v147
	v_mov_b32_e32 v173, v1
	v_mov_b32_e32 v177, v1
	v_mov_b32_e32 v135, v0
	v_mov_b32_e32 v193, v192
	v_mov_b32_e32 v146, 0
	s_mov_b32 s11, 0
	v_bitop3_b32 v140, v180, v3, 32 bitop3:0x36
	v_bitop3_b32 v141, v180, v3, 64 bitop3:0x36
	v_bitop3_b32 v142, v180, v3, s4 bitop3:0x36
	v_cmp_gt_u32_e64 s[4:5], 32, v155
	v_lshl_add_u32 v3, v143, 2, s13
	v_lshlrev_b32_e32 v4, 6, v147
	v_or3_b32 v2, s12, v2, v144
	s_add_i32 s60, 0, 0x14000
	v_mov_b32_e32 v175, v1
	v_mov_b32_e32 v179, v1
	v_permlane32_swap_b32_e32 v0, v135
	v_permlane32_swap_b32_e32 v192, v193
	v_xor_b32_e32 v148, 0x80000000, v195
	v_lshl_add_u64 v[130:131], s[14:15], 0, v[172:173]
	v_lshl_add_u64 v[132:133], s[14:15], 0, v[176:177]
	s_add_i32 s52, s52, 0x10800
	v_lshlrev_b32_e32 v137, 8, v143
	v_sub_u32_e32 v149, v143, v4
	v_add_u32_e32 v150, s60, v2
	v_lshlrev_b32_e32 v66, 2, v143
	v_xor_b32_e32 v150, v66, v150
	s_mov_b64 s[42:43], 0
	s_xor_b64 s[12:13], s[4:5], -1
	v_add_u32_e32 v152, s59, v3
	s_mov_b32 s61, s54
	s_mov_b32 s53, s11
	v_mov_b32_e32 v2, 0
	v_mov_b32_e32 v3, v146
	v_mov_b32_e32 v4, v146
	v_mov_b32_e32 v5, v146
	v_mov_b32_e32 v6, v146
	v_mov_b32_e32 v7, v146
	v_mov_b32_e32 v8, v146
	v_mov_b32_e32 v9, v146
	v_mov_b32_e32 v10, v146
	v_mov_b32_e32 v11, v146
	v_mov_b32_e32 v12, v146
	v_mov_b32_e32 v13, v146
	v_mov_b32_e32 v14, v146
	v_mov_b32_e32 v15, v146
	v_mov_b32_e32 v16, v146
	v_mov_b32_e32 v17, v146
	v_mov_b32_e32 v18, 0
	v_mov_b32_e32 v19, v146
	v_mov_b32_e32 v20, v146
	v_mov_b32_e32 v21, v146
	v_mov_b32_e32 v22, v146
	v_mov_b32_e32 v23, v146
	v_mov_b32_e32 v24, v146
	v_mov_b32_e32 v25, v146
	v_mov_b32_e32 v26, v146
	v_mov_b32_e32 v27, v146
	v_mov_b32_e32 v28, v146
	v_mov_b32_e32 v29, v146
	v_mov_b32_e32 v30, v146
	v_mov_b32_e32 v31, v146
	v_mov_b32_e32 v32, v146
	v_mov_b32_e32 v33, v146
	v_mov_b32_e32 v34, 0
	v_mov_b32_e32 v35, v146
	v_mov_b32_e32 v36, v146
	v_mov_b32_e32 v37, v146
	v_mov_b32_e32 v38, v146
	v_mov_b32_e32 v39, v146
	v_mov_b32_e32 v40, v146
	v_mov_b32_e32 v41, v146
	v_mov_b32_e32 v42, v146
	v_mov_b32_e32 v43, v146
	v_mov_b32_e32 v44, v146
	v_mov_b32_e32 v45, v146
	v_mov_b32_e32 v46, v146
	v_mov_b32_e32 v47, v146
	v_mov_b32_e32 v48, v146
	v_mov_b32_e32 v49, v146
	v_mov_b32_e32 v50, 0
	v_mov_b32_e32 v51, v146
	v_mov_b32_e32 v52, v146
	v_mov_b32_e32 v53, v146
	v_mov_b32_e32 v54, v146
	v_mov_b32_e32 v55, v146
	v_mov_b32_e32 v56, v146
	v_mov_b32_e32 v57, v146
	v_mov_b32_e32 v58, v146
	v_mov_b32_e32 v59, v146
	v_mov_b32_e32 v60, v146
	v_mov_b32_e32 v61, v146
	v_mov_b32_e32 v62, v146
	v_mov_b32_e32 v63, v146
	v_mov_b32_e32 v64, v146
	v_mov_b32_e32 v65, v146
	v_and_b32_e32 v66, 8, v143
	v_lshlrev_b32_e32 v66, 4, v66
	v_xor_b32_e32 v138, v66, v138
	v_xor_b32_e32 v140, v66, v140
	v_xor_b32_e32 v141, v66, v141
	v_xor_b32_e32 v142, v66, v142
	s_barrier

.LBB0_1706:
	s_nop 9
	v_add_f32_e32 v71, v162, v71
	v_add_f32_e32 v66, v162, v66
	v_exp_f32_e32 v158, v71
	v_add_f32_e32 v71, v87, v162
	v_exp_f32_e32 v153, v66
	v_add_f32_e32 v66, v82, v162
	v_add_f32_e32 v69, v162, v69
	v_exp_f32_e32 v82, v71
	v_add_f32_e32 v71, v162, v72
	v_add_f32_e32 v67, v162, v67
	v_exp_f32_e32 v157, v69
	v_exp_f32_e32 v160, v71
	v_add_f32_e32 v71, v88, v162
	v_exp_f32_e32 v154, v67
	v_add_f32_e32 v67, v83, v162
	v_exp_f32_e32 v83, v71
	v_add_f32_e32 v71, v162, v73
	v_add_f32_e32 v68, v162, v68
	v_exp_f32_e32 v161, v71
	v_add_f32_e32 v71, v89, v162
	v_exp_f32_e32 v156, v68
	v_add_f32_e32 v68, v84, v162
	v_add_f32_e32 v70, v162, v70
	v_exp_f32_e32 v84, v71
	v_add_f32_e32 v71, v162, v74
	v_add_f32_e32 v72, v162, v75
	v_add_f32_e32 v75, v162, v78
	v_add_f32_e32 v69, v85, v162
	v_exp_f32_e32 v85, v70
	v_add_f32_e32 v70, v86, v162
	v_exp_f32_e32 v86, v71
	v_add_f32_e32 v71, v90, v162
	v_add_f32_e32 v73, v162, v76
	v_exp_f32_e32 v90, v75
	v_add_f32_e32 v75, v94, v162
	v_add_f32_e32 v76, v162, v79
	v_mul_f32_e32 v94, 0.5, v157
	v_add_f32_e32 v74, v162, v77
	v_exp_f32_e32 v79, v76
	v_add_f32_e32 v76, v95, v162
	v_mov_b32_e32 v95, v94
	v_exp_f32_e32 v89, v74
	v_add_f32_e32 v74, v93, v162
	v_add_f32_e32 v77, v162, v80
	v_add_f32_e32 v93, v153, v154
	v_permlane32_swap_b32_e32 v94, v95
	v_exp_f32_e32 v80, v77
	v_add_f32_e32 v77, v96, v162
	v_add_f32_e32 v78, v162, v81
	v_add_f32_e32 v93, v156, v93
	v_cndmask_b32_e64 v94, v94, v95, s[4:5]
	v_mul_f32_e32 v96, 0.5, v161
	v_exp_f32_e32 v81, v78
	v_add_f32_e32 v78, v97, v162
	v_fmac_f32_e32 v93, 0.5, v157
	v_cndmask_b32_e64 v95, v94, 0, s[4:5]
	v_mov_b32_e32 v97, v96
	v_add_f32_e32 v93, v93, v95
	v_add_f32_e32 v95, v85, v158
	v_permlane32_swap_b32_e32 v96, v97
	v_add_f32_e32 v95, v160, v95
	v_cndmask_b32_e64 v96, v96, v97, s[4:5]
	v_fmac_f32_e32 v95, 0.5, v161
	v_cndmask_b32_e64 v94, v96, v94, s[4:5]
	v_exp_f32_e32 v87, v72
	v_add_f32_e32 v94, v95, v94
	v_exp_f32_e32 v88, v73
	ds_write_b32 v150, v93
	v_xor_b32_e32 v251, 8, v150
	ds_write_b32 v251, v94
	v_mul_f32_e32 v94, 0.5, v89
	v_mov_b32_e32 v95, v94
	s_nop 1
	v_permlane32_swap_b32_e32 v94, v95
	v_add_f32_e32 v93, v86, v87
	v_cndmask_b32_e64 v94, v94, v95, s[4:5]
	v_add_f32_e32 v93, v88, v93
	v_cndmask_b32_e64 v95, v94, v96, s[4:5]
	v_mul_f32_e32 v96, 0.5, v81
	v_fmac_f32_e32 v93, 0.5, v89
	v_mov_b32_e32 v97, v96
	v_exp_f32_e32 v69, v69
	v_add_f32_e32 v93, v93, v95
	v_add_f32_e32 v95, v90, v79
	v_permlane32_swap_b32_e32 v96, v97
	v_add_f32_e32 v95, v80, v95
	v_cndmask_b32_e64 v96, v96, v97, s[4:5]
	v_fmac_f32_e32 v95, 0.5, v81
	v_cndmask_b32_e64 v94, v96, v94, s[4:5]
	v_exp_f32_e32 v66, v66
	v_exp_f32_e32 v67, v67
	v_add_f32_e32 v94, v95, v94
	v_exp_f32_e32 v68, v68
	v_xor_b32_e32 v251, 16, v150
	ds_write_b32 v251, v93
	v_xor_b32_e32 v251, 24, v150
	ds_write_b32 v251, v94
	v_mul_f32_e32 v94, 0.5, v69
	v_mov_b32_e32 v95, v94
	v_exp_f32_e32 v70, v70
	s_nop 0
	v_permlane32_swap_b32_e32 v94, v95
	v_add_f32_e32 v72, v91, v162
	v_add_f32_e32 v91, v153, v66
	v_add_f32_e32 v93, v66, v67
	v_cndmask_b32_e64 v94, v94, v95, s[4:5]
	v_add_f32_e32 v73, v92, v162
	v_add_f32_e32 v91, 0, v91
	v_add_f32_e32 v92, v154, v67
	v_add_f32_e32 v93, v68, v93
	v_cndmask_b32_e64 v95, v94, v96, s[4:5]
	v_mul_f32_e32 v96, 0.5, v84
	v_add_f32_e32 v91, v92, v91
	v_add_f32_e32 v92, v156, v68
	v_fmac_f32_e32 v93, 0.5, v69
	v_mov_b32_e32 v97, v96
	v_exp_f32_e32 v74, v74
	v_add_f32_e32 v91, v92, v91
	v_add_f32_e32 v92, v157, v69
	v_add_f32_e32 v93, v93, v95
	v_add_f32_e32 v95, v70, v82
	v_permlane32_swap_b32_e32 v96, v97
	v_exp_f32_e32 v71, v71
	v_add_f32_e32 v91, v92, v91
	v_add_f32_e32 v92, v85, v70
	v_add_f32_e32 v95, v83, v95
	v_cndmask_b32_e64 v96, v96, v97, s[4:5]
	v_exp_f32_e32 v72, v72
	v_add_f32_e32 v91, v92, v91
	v_add_f32_e32 v92, v158, v82
	v_fmac_f32_e32 v95, 0.5, v84
	v_cndmask_b32_e64 v94, v96, v94, s[4:5]
	v_exp_f32_e32 v73, v73
	v_add_f32_e32 v91, v92, v91
	v_add_f32_e32 v92, v160, v83
	v_add_f32_e32 v94, v95, v94
	v_add_f32_e32 v91, v92, v91
	v_add_f32_e32 v92, v161, v84
	v_xor_b32_e32 v251, 32, v150
	ds_write_b32 v251, v93
	v_xor_b32_e32 v251, 40, v150
	ds_write_b32 v251, v94
	v_mul_f32_e32 v94, 0.5, v74
	v_exp_f32_e32 v75, v75
	v_exp_f32_e32 v76, v76
	v_add_f32_e32 v91, v92, v91
	v_add_f32_e32 v92, v86, v71
	v_mov_b32_e32 v95, v94
	v_exp_f32_e32 v77, v77
	v_exp_f32_e32 v78, v78
	v_add_f32_e32 v91, v92, v91
	v_add_f32_e32 v92, v87, v72
	v_add_f32_e32 v93, v71, v72
	v_permlane32_swap_b32_e32 v94, v95
	v_add_f32_e32 v91, v92, v91
	v_add_f32_e32 v92, v88, v73
	v_add_f32_e32 v93, v73, v93
	v_cndmask_b32_e64 v94, v94, v95, s[4:5]
	v_add_f32_e32 v91, v92, v91
	v_add_f32_e32 v92, v89, v74
	v_fmac_f32_e32 v93, 0.5, v74
	v_cndmask_b32_e64 v95, v94, v96, s[4:5]
	v_add_f32_e32 v91, v92, v91
	v_add_f32_e32 v92, v90, v75
	v_add_f32_e32 v95, v93, v95
	v_add_f32_e32 v93, v75, v76
	v_add_f32_e32 v91, v92, v91
	v_add_f32_e32 v92, v79, v76
	v_add_f32_e32 v96, v77, v93
	v_mul_f32_e32 v93, 0.5, v78
	v_add_f32_e32 v91, v92, v91
	v_add_f32_e32 v92, v80, v77
	v_mov_b32_e32 v97, v93
	v_mov_b32_e32 v159, v93
	v_add_f32_e32 v91, v92, v91
	v_add_f32_e32 v92, v81, v78
	v_permlane32_swap_b32_e32 v97, v159
	v_add_f32_e32 v91, v92, v91
	s_cmp_eq_u32 s42, 0
	v_cndmask_b32_e64 v97, v97, v159, s[4:5]
	v_mov_b32_e32 v92, v91
	s_cselect_b64 s[42:43], -1, 0
	v_fmac_f32_e32 v96, 0.5, v78
	v_cndmask_b32_e64 v94, v97, v94, s[4:5]
	v_permlane32_swap_b32_e32 v91, v92
	s_and_b64 s[44:45], s[12:13], s[42:43]
	v_add_f32_e32 v94, v96, v94
	v_xor_b32_e32 v251, 48, v150
	ds_write_b32 v251, v95
	v_xor_b32_e32 v251, 56, v150
	ds_write_b32 v251, v94
	s_and_saveexec_b64 s[42:43], s[44:45]
	ds_write_b32 v152, v93
	s_or_b64 exec, exec, s[42:43]
	v_add_f32_e32 v91, v91, v92
	v_cvt_pk_bf16_f32 v92, v153, v154
	v_cvt_pk_bf16_f32 v93, v156, v157
	v_cvt_pk_bf16_f32 v94, v85, v158
	v_cvt_pk_bf16_f32 v95, v160, v161
	v_cvt_pk_bf16_f32 v86, v86, v87
	v_cvt_pk_bf16_f32 v87, v88, v89
	v_cvt_pk_bf16_f32 v88, v90, v79
	v_cvt_pk_bf16_f32 v89, v80, v81
	v_cvt_pk_bf16_f32 v66, v66, v67
	v_cvt_pk_bf16_f32 v67, v68, v69
	v_cvt_pk_bf16_f32 v68, v70, v82
	v_cvt_pk_bf16_f32 v69, v83, v84
	v_cvt_pk_bf16_f32 v70, v71, v72
	v_cvt_pk_bf16_f32 v71, v73, v74
	v_cvt_pk_bf16_f32 v72, v75, v76
	v_cvt_pk_bf16_f32 v73, v77, v78
	v_add_u32_e32 v153, s62, v181
	ds_read_b64_tr_b16 v[74:75], v153 offset:0
	ds_read_b64_tr_b16 v[76:77], v153 offset:0x800
	ds_read_b64_tr_b16 v[78:79], v153 offset:0x200
	ds_read_b64_tr_b16 v[80:81], v153 offset:0xa00
	ds_read_b64_tr_b16 v[82:83], v153 offset:0x400
	ds_read_b64_tr_b16 v[84:85], v153 offset:0xc00
	ds_read_b64_tr_b16 v[156:157], v153 offset:0x600
	ds_read_b64_tr_b16 v[158:159], v153 offset:0xe00
	ds_read_b64_tr_b16 v[164:165], v153 offset:0x1000
	ds_read_b64_tr_b16 v[166:167], v153 offset:0x1800
	ds_read_b64_tr_b16 v[196:197], v153 offset:0x1200
	ds_read_b64_tr_b16 v[198:199], v153 offset:0x1a00
	ds_read_b64_tr_b16 v[200:201], v153 offset:0x1400
	ds_read_b64_tr_b16 v[202:203], v153 offset:0x1c00
	ds_read_b64_tr_b16 v[204:205], v153 offset:0x1600
	ds_read_b64_tr_b16 v[206:207], v153 offset:0x1e00
	s_waitcnt lgkmcnt(8)
	v_add_f32_e32 v146, v146, v91
	v_permlane32_swap_b32_e32 v92, v94
	v_permlane32_swap_b32_e32 v93, v95
	v_permlane32_swap_b32_e32 v86, v88
	v_permlane32_swap_b32_e32 v87, v89
	v_permlane32_swap_b32_e32 v66, v68
	v_permlane32_swap_b32_e32 v67, v69
	v_permlane32_swap_b32_e32 v70, v72
	v_permlane32_swap_b32_e32 v71, v73
	v_mfma_f32_32x32x16_bf16 v[50:65], v[92:95], v[74:77], v[50:65]
	v_mfma_f32_32x32x16_bf16 v[34:49], v[92:95], v[78:81], v[34:49]
	v_mfma_f32_32x32x16_bf16 v[18:33], v[92:95], v[82:85], v[18:33]
	v_mfma_f32_32x32x16_bf16 v[2:17], v[92:95], v[156:159], v[2:17]
	ds_read_b64_tr_b16 v[74:75], v153 offset:0x2000
	ds_read_b64_tr_b16 v[76:77], v153 offset:0x2800
	ds_read_b64_tr_b16 v[78:79], v153 offset:0x2200
	ds_read_b64_tr_b16 v[80:81], v153 offset:0x2a00
	ds_read_b64_tr_b16 v[82:83], v153 offset:0x2400
	ds_read_b64_tr_b16 v[84:85], v153 offset:0x2c00
	ds_read_b64_tr_b16 v[90:91], v153 offset:0x2600
	ds_read_b64_tr_b16 v[92:93], v153 offset:0x2e00
	s_waitcnt lgkmcnt(8)
	v_mfma_f32_32x32x16_bf16 v[50:65], v[86:89], v[164:167], v[50:65]
	v_mfma_f32_32x32x16_bf16 v[34:49], v[86:89], v[196:199], v[34:49]
	v_mfma_f32_32x32x16_bf16 v[18:33], v[86:89], v[200:203], v[18:33]
	v_mfma_f32_32x32x16_bf16 v[2:17], v[86:89], v[204:207], v[2:17]
	ds_read_b64_tr_b16 v[86:87], v153 offset:0x3000
	ds_read_b64_tr_b16 v[88:89], v153 offset:0x3800
	ds_read_b64_tr_b16 v[94:95], v153 offset:0x3200
	ds_read_b64_tr_b16 v[96:97], v153 offset:0x3a00
	ds_read_b64_tr_b16 v[156:157], v153 offset:0x3400
	ds_read_b64_tr_b16 v[158:159], v153 offset:0x3c00
	ds_read_b64_tr_b16 v[164:165], v153 offset:0x3600
	ds_read_b64_tr_b16 v[166:167], v153 offset:0x3e00
	s_waitcnt lgkmcnt(8)
	v_mfma_f32_32x32x16_bf16 v[50:65], v[66:69], v[74:77], v[50:65]
	v_mfma_f32_32x32x16_bf16 v[34:49], v[66:69], v[78:81], v[34:49]
	v_mfma_f32_32x32x16_bf16 v[18:33], v[66:69], v[82:85], v[18:33]
	v_mfma_f32_32x32x16_bf16 v[2:17], v[66:69], v[90:93], v[2:17]
	s_waitcnt lgkmcnt(0)
	v_mfma_f32_32x32x16_bf16 v[50:65], v[70:73], v[86:89], v[50:65]
	s_waitcnt lgkmcnt(0)
	s_xor_b32 s53, s53, 1
	s_addk_i32 s61, 0xfc00
	v_xor_b32_e32 v150, 64, v150
	s_andn2_b64 vcc, exec, s[40:41]
	v_mfma_f32_32x32x16_bf16 v[34:49], v[70:73], v[94:97], v[34:49]
	v_mfma_f32_32x32x16_bf16 v[18:33], v[70:73], v[156:159], v[18:33]
	v_mfma_f32_32x32x16_bf16 v[2:17], v[70:73], v[164:167], v[2:17]
	s_cbranch_vccz .LBB0_1710
	s_mov_b64 s[42:43], s[18:19]
	s_branch .LBB0_1698

.LBB0_1716:
	s_andn2_b64 vcc, exec, s[10:11]
	s_cbranch_vccnz .LBB0_1970
	s_lshl_b32 s6, s3, 2
	v_or_b32_e32 v70, s6, v147
	v_xor_b32_e32 v71, v70, v143
	v_lshl_add_u32 v71, v71, 2, s60
	v_lshl_add_u32 v72, v70, 2, 0
	v_lshl_add_u32 v68, v70, 7, v71
	v_add_u32_e32 v69, 0x1c000, v72
	v_add_u32_e32 v67, 0x1c400, v72
	v_add_u32_e32 v73, 0x1c480, v72
	v_add_u32_e32 v90, 0x1c500, v72
	v_add_u32_e32 v91, 0x1c580, v72
	v_add_u32_e32 v92, 0x1c600, v72
	v_add_u32_e32 v93, 0x1c680, v72
	v_add_u32_e32 v94, 0x1c700, v72
	v_add_u32_e32 v95, 0x1c780, v72
	ds_read2st64_b32 v[74:75], v68 offset1:16
	ds_read2_b32 v[76:77], v69 offset1:32
	ds_read2st64_b32 v[78:79], v68 offset0:32 offset1:48
	ds_read2_b32 v[80:81], v69 offset0:64 offset1:96
	ds_read2st64_b32 v[82:83], v68 offset0:64 offset1:80
	ds_read2_b32 v[84:85], v69 offset0:128 offset1:160
	ds_read2st64_b32 v[86:87], v68 offset0:96 offset1:112
	ds_read2_b32 v[88:89], v69 offset0:192 offset1:224
	ds_read_b32 v67, v67
	ds_read_b32 v73, v73
	ds_read_b32 v90, v90
	ds_read_b32 v91, v91
	ds_read_b32 v92, v92
	ds_read_b32 v93, v93
	ds_read_b32 v94, v94
	ds_read_b32 v95, v95
	v_cmp_eq_u32_e64 s[8:9], 16, v143
	v_cmp_eq_u32_e32 vcc, 0, v143
	s_waitcnt lgkmcnt(0)
	v_cndmask_b32_e64 v76, 0, v76, s[8:9]
	v_add_f32_e32 v74, v74, v76
	v_fma_f32 v67, v67, v74, 0
	v_cndmask_b32_e64 v74, 0, v77, s[8:9]
	v_add_f32_e32 v74, v75, v74
	v_fmac_f32_e32 v67, v73, v74
	v_cndmask_b32_e64 v73, 0, v80, s[8:9]
	v_add_f32_e32 v73, v78, v73
	v_fmac_f32_e32 v67, v90, v73
	v_cndmask_b32_e64 v73, 0, v81, s[8:9]
	v_add_f32_e32 v73, v79, v73
	v_fmac_f32_e32 v67, v91, v73
	v_cndmask_b32_e64 v73, 0, v84, s[8:9]
	v_add_f32_e32 v73, v82, v73
	v_fmac_f32_e32 v67, v92, v73
	v_cndmask_b32_e64 v73, 0, v85, s[8:9]
	v_add_f32_e32 v73, v83, v73
	s_add_i32 s6, s6, s54
	v_fmac_f32_e32 v67, v93, v73
	v_cndmask_b32_e64 v73, 0, v88, s[8:9]
	s_ashr_i32 s12, s6, 6
	v_add_f32_e32 v73, v86, v73
	v_cmp_eq_u32_e64 s[6:7], s12, v143
	v_fmac_f32_e32 v67, v94, v73
	v_cndmask_b32_e64 v73, 0, v89, s[8:9]
	s_or_b64 s[10:11], vcc, s[6:7]
	s_add_i32 s6, s12, -1
	v_add_f32_e32 v73, v87, v73
	v_cmp_eq_u32_e64 s[6:7], s6, v143
	v_fmac_f32_e32 v67, v95, v73
	s_or_b64 s[10:11], s[10:11], s[6:7]
	v_cmp_ge_i32_e64 s[6:7], s12, v143
	s_nop 1
	v_cndmask_b32_e64 v67, v187, v67, s[6:7]
	v_cndmask_b32_e64 v73, v67, v188, s[10:11]
	v_lshlrev_b32_e32 v67, 2, v194
	ds_bpermute_b32 v77, v67, v73
	ds_bpermute_b32 v76, v67, v73 offset:4
	ds_bpermute_b32 v79, v67, v73 offset:8
	ds_bpermute_b32 v78, v67, v73 offset:12
	ds_bpermute_b32 v81, v67, v73 offset:16
	ds_bpermute_b32 v80, v67, v73 offset:20
	ds_bpermute_b32 v83, v67, v73 offset:24
	ds_bpermute_b32 v82, v67, v73 offset:28
	ds_bpermute_b32 v85, v67, v73 offset:32
	ds_bpermute_b32 v84, v67, v73 offset:36
	ds_bpermute_b32 v87, v67, v73 offset:40
	ds_bpermute_b32 v86, v67, v73 offset:44
	ds_bpermute_b32 v89, v67, v73 offset:48
	ds_bpermute_b32 v88, v67, v73 offset:52
	ds_bpermute_b32 v91, v67, v73 offset:56
	ds_bpermute_b32 v90, v67, v73 offset:60
	s_waitcnt lgkmcnt(0)
	v_mov_b32_e32 v74, 1
	v_cmp_lt_f32_e64 s[12:13], v73, v77
	v_cmp_eq_f32_e64 s[18:19], v73, v77
	v_cmp_ne_u32_e64 s[36:37], 0, v143
	s_and_b64 s[18:19], s[18:19], s[36:37]
	s_or_b64 s[12:13], s[12:13], s[18:19]
	v_cndmask_b32_e64 v75, 0, 1, s[12:13]
	v_cmp_lt_f32_e64 s[12:13], v73, v76
	v_cmp_eq_f32_e64 s[18:19], v73, v76
	v_cmp_lt_u32_e64 s[36:37], 1, v143
	s_and_b64 s[18:19], s[18:19], s[36:37]
	s_or_b64 s[12:13], s[12:13], s[18:19]
	v_cndmask_b32_e64 v74, 0, 1, s[12:13]
	v_mov_b32_e32 v76, 1
	v_cmp_lt_f32_e64 s[12:13], v73, v79
	v_cmp_eq_f32_e64 s[18:19], v73, v79
	v_cmp_lt_u32_e64 s[36:37], 2, v143
	s_and_b64 s[18:19], s[18:19], s[36:37]
	s_or_b64 s[12:13], s[12:13], s[18:19]
	v_cndmask_b32_e64 v77, 0, 1, s[12:13]
	v_cmp_lt_f32_e64 s[12:13], v73, v78
	v_cmp_eq_f32_e64 s[18:19], v73, v78
	v_cmp_lt_u32_e64 s[36:37], 3, v143
	s_and_b64 s[18:19], s[18:19], s[36:37]
	s_or_b64 s[12:13], s[12:13], s[18:19]
	v_cndmask_b32_e64 v76, 0, 1, s[12:13]
	v_mov_b32_e32 v78, 1
	v_cmp_lt_f32_e64 s[12:13], v73, v81
	v_cmp_eq_f32_e64 s[18:19], v73, v81
	v_cmp_lt_u32_e64 s[36:37], 4, v143
	s_and_b64 s[18:19], s[18:19], s[36:37]
	s_or_b64 s[12:13], s[12:13], s[18:19]
	v_cndmask_b32_e64 v79, 0, 1, s[12:13]
	v_cmp_lt_f32_e64 s[12:13], v73, v80
	v_cmp_eq_f32_e64 s[18:19], v73, v80
	v_cmp_lt_u32_e64 s[36:37], 5, v143
	s_and_b64 s[18:19], s[18:19], s[36:37]
	s_or_b64 s[12:13], s[12:13], s[18:19]
	v_cndmask_b32_e64 v78, 0, 1, s[12:13]
	v_mov_b32_e32 v80, 1
	v_cmp_lt_f32_e64 s[12:13], v73, v83
	v_cmp_eq_f32_e64 s[18:19], v73, v83
	v_cmp_lt_u32_e64 s[36:37], 6, v143
	s_and_b64 s[18:19], s[18:19], s[36:37]
	s_or_b64 s[12:13], s[12:13], s[18:19]
	v_cndmask_b32_e64 v81, 0, 1, s[12:13]
	v_cmp_lt_f32_e64 s[12:13], v73, v82
	v_cmp_eq_f32_e64 s[18:19], v73, v82
	v_cmp_lt_u32_e64 s[36:37], 7, v143
	s_and_b64 s[18:19], s[18:19], s[36:37]
	s_or_b64 s[12:13], s[12:13], s[18:19]
	v_cndmask_b32_e64 v80, 0, 1, s[12:13]
	v_mov_b32_e32 v82, 1
	v_cmp_lt_f32_e64 s[12:13], v73, v85
	v_cmp_eq_f32_e64 s[18:19], v73, v85
	v_cmp_lt_u32_e64 s[36:37], 8, v143
	s_and_b64 s[18:19], s[18:19], s[36:37]
	s_or_b64 s[12:13], s[12:13], s[18:19]
	v_cndmask_b32_e64 v83, 0, 1, s[12:13]
	v_cmp_lt_f32_e64 s[12:13], v73, v84
	v_cmp_eq_f32_e64 s[18:19], v73, v84
	v_cmp_lt_u32_e64 s[36:37], 9, v143
	s_and_b64 s[18:19], s[18:19], s[36:37]
	s_or_b64 s[12:13], s[12:13], s[18:19]
	v_cndmask_b32_e64 v82, 0, 1, s[12:13]
	v_mov_b32_e32 v84, 1
	v_cmp_lt_f32_e64 s[12:13], v73, v87
	v_cmp_eq_f32_e64 s[18:19], v73, v87
	v_cmp_lt_u32_e64 s[36:37], 10, v143
	s_and_b64 s[18:19], s[18:19], s[36:37]
	s_or_b64 s[12:13], s[12:13], s[18:19]
	v_cndmask_b32_e64 v85, 0, 1, s[12:13]
	v_cmp_lt_f32_e64 s[12:13], v73, v86
	v_cmp_eq_f32_e64 s[18:19], v73, v86
	v_cmp_lt_u32_e64 s[36:37], 11, v143
	s_and_b64 s[18:19], s[18:19], s[36:37]
	s_or_b64 s[12:13], s[12:13], s[18:19]
	v_cndmask_b32_e64 v84, 0, 1, s[12:13]
	v_mov_b32_e32 v86, 1
	v_cmp_lt_f32_e64 s[12:13], v73, v89
	v_cmp_eq_f32_e64 s[18:19], v73, v89
	v_cmp_lt_u32_e64 s[36:37], 12, v143
	s_and_b64 s[18:19], s[18:19], s[36:37]
	s_or_b64 s[12:13], s[12:13], s[18:19]
	v_cndmask_b32_e64 v87, 0, 1, s[12:13]
	v_cmp_lt_f32_e64 s[12:13], v73, v88
	v_cmp_eq_f32_e64 s[18:19], v73, v88
	v_cmp_lt_u32_e64 s[36:37], 13, v143
	s_and_b64 s[18:19], s[18:19], s[36:37]
	s_or_b64 s[12:13], s[12:13], s[18:19]
	v_cndmask_b32_e64 v86, 0, 1, s[12:13]
	v_mov_b32_e32 v88, 1
	v_cmp_lt_f32_e64 s[12:13], v73, v91
	v_cmp_eq_f32_e64 s[18:19], v73, v91
	v_cmp_lt_u32_e64 s[36:37], 14, v143
	s_and_b64 s[18:19], s[18:19], s[36:37]
	s_or_b64 s[12:13], s[12:13], s[18:19]
	v_cndmask_b32_e64 v89, 0, 1, s[12:13]
	v_cmp_lt_f32_e64 s[12:13], v73, v90
	v_cmp_eq_f32_e64 s[18:19], v73, v90
	v_cmp_lt_u32_e64 s[36:37], 15, v143
	s_and_b64 s[18:19], s[18:19], s[36:37]
	s_or_b64 s[12:13], s[12:13], s[18:19]
	v_cndmask_b32_e64 v88, 0, 1, s[12:13]
	ds_bpermute_b32 v96, v67, v73 offset:64
	ds_bpermute_b32 v95, v67, v73 offset:68
	ds_bpermute_b32 v132, v67, v73 offset:72
	ds_bpermute_b32 v131, v67, v73 offset:76
	ds_bpermute_b32 v149, v67, v73 offset:80
	ds_bpermute_b32 v148, v67, v73 offset:84
	ds_bpermute_b32 v153, v67, v73 offset:88
	ds_bpermute_b32 v152, v67, v73 offset:92
	ds_bpermute_b32 v150, v67, v73 offset:96
	ds_bpermute_b32 v146, v67, v73 offset:100
	ds_bpermute_b32 v133, v67, v73 offset:104
	ds_bpermute_b32 v130, v67, v73 offset:108
	ds_bpermute_b32 v97, v67, v73 offset:112
	ds_bpermute_b32 v94, v67, v73 offset:116
	ds_bpermute_b32 v93, v67, v73 offset:120
	ds_bpermute_b32 v90, v67, v73 offset:124
	s_waitcnt lgkmcnt(0)
	v_mov_b32_e32 v91, 1
	v_cmp_lt_f32_e64 s[12:13], v73, v96
	v_cmp_eq_f32_e64 s[18:19], v73, v96
	v_cmp_lt_u32_e64 s[36:37], 16, v143
	s_and_b64 s[18:19], s[18:19], s[36:37]
	s_or_b64 s[12:13], s[12:13], s[18:19]
	v_cndmask_b32_e64 v92, 0, 1, s[12:13]
	v_cmp_lt_f32_e64 s[12:13], v73, v95
	v_cmp_eq_f32_e64 s[18:19], v73, v95
	v_cmp_lt_u32_e64 s[36:37], 17, v143
	s_and_b64 s[18:19], s[18:19], s[36:37]
	s_or_b64 s[12:13], s[12:13], s[18:19]
	v_cndmask_b32_e64 v91, 0, 1, s[12:13]
	v_mov_b32_e32 v95, 1
	v_cmp_lt_f32_e64 s[12:13], v73, v132
	v_cmp_eq_f32_e64 s[18:19], v73, v132
	v_cmp_lt_u32_e64 s[36:37], 18, v143
	s_and_b64 s[18:19], s[18:19], s[36:37]
	s_or_b64 s[12:13], s[12:13], s[18:19]
	v_cndmask_b32_e64 v96, 0, 1, s[12:13]
	v_cmp_lt_f32_e64 s[12:13], v73, v131
	v_cmp_eq_f32_e64 s[18:19], v73, v131
	v_cmp_lt_u32_e64 s[36:37], 19, v143
	s_and_b64 s[18:19], s[18:19], s[36:37]
	s_or_b64 s[12:13], s[12:13], s[18:19]
	v_cndmask_b32_e64 v95, 0, 1, s[12:13]
	v_mov_b32_e32 v131, 1
	v_cmp_lt_f32_e64 s[12:13], v73, v149
	v_cmp_eq_f32_e64 s[18:19], v73, v149
	v_cmp_lt_u32_e64 s[36:37], 20, v143
	s_and_b64 s[18:19], s[18:19], s[36:37]
	s_or_b64 s[12:13], s[12:13], s[18:19]
	v_cndmask_b32_e64 v132, 0, 1, s[12:13]
	v_cmp_lt_f32_e64 s[12:13], v73, v148
	v_cmp_eq_f32_e64 s[18:19], v73, v148
	v_cmp_lt_u32_e64 s[36:37], 21, v143
	s_and_b64 s[18:19], s[18:19], s[36:37]
	s_or_b64 s[12:13], s[12:13], s[18:19]
	v_cndmask_b32_e64 v131, 0, 1, s[12:13]
	v_mov_b32_e32 v148, 1
	v_cmp_lt_f32_e64 s[12:13], v73, v153
	v_cmp_eq_f32_e64 s[18:19], v73, v153
	v_cmp_lt_u32_e64 s[36:37], 22, v143
	s_and_b64 s[18:19], s[18:19], s[36:37]
	s_or_b64 s[12:13], s[12:13], s[18:19]
	v_cndmask_b32_e64 v149, 0, 1, s[12:13]
	v_cmp_lt_f32_e64 s[12:13], v73, v152
	v_cmp_eq_f32_e64 s[18:19], v73, v152
	v_cmp_lt_u32_e64 s[36:37], 23, v143
	s_and_b64 s[18:19], s[18:19], s[36:37]
	s_or_b64 s[12:13], s[12:13], s[18:19]
	v_cndmask_b32_e64 v148, 0, 1, s[12:13]
	v_mov_b32_e32 v152, 1
	v_cmp_lt_f32_e64 s[12:13], v73, v150
	v_cmp_eq_f32_e64 s[18:19], v73, v150
	v_cmp_lt_u32_e64 s[36:37], 24, v143
	s_and_b64 s[18:19], s[18:19], s[36:37]
	s_or_b64 s[12:13], s[12:13], s[18:19]
	v_cndmask_b32_e64 v153, 0, 1, s[12:13]
	v_cmp_lt_f32_e64 s[12:13], v73, v146
	v_cmp_eq_f32_e64 s[18:19], v73, v146
	v_cmp_lt_u32_e64 s[36:37], 25, v143
	s_and_b64 s[18:19], s[18:19], s[36:37]
	s_or_b64 s[12:13], s[12:13], s[18:19]
	v_cndmask_b32_e64 v152, 0, 1, s[12:13]
	v_mov_b32_e32 v146, 1
	v_cmp_lt_f32_e64 s[12:13], v73, v133
	v_cmp_eq_f32_e64 s[18:19], v73, v133
	v_cmp_lt_u32_e64 s[36:37], 26, v143
	s_and_b64 s[18:19], s[18:19], s[36:37]
	s_or_b64 s[12:13], s[12:13], s[18:19]
	v_cndmask_b32_e64 v150, 0, 1, s[12:13]
	v_cmp_lt_f32_e64 s[12:13], v73, v130
	v_cmp_eq_f32_e64 s[18:19], v73, v130
	v_cmp_lt_u32_e64 s[36:37], 27, v143
	s_and_b64 s[18:19], s[18:19], s[36:37]
	s_or_b64 s[12:13], s[12:13], s[18:19]
	v_cndmask_b32_e64 v146, 0, 1, s[12:13]
	v_mov_b32_e32 v130, 1
	v_cmp_lt_f32_e64 s[12:13], v73, v97
	v_cmp_eq_f32_e64 s[18:19], v73, v97
	v_cmp_lt_u32_e64 s[36:37], 28, v143
	s_and_b64 s[18:19], s[18:19], s[36:37]
	s_or_b64 s[12:13], s[12:13], s[18:19]
	v_cndmask_b32_e64 v133, 0, 1, s[12:13]
	v_cmp_lt_f32_e64 s[12:13], v73, v94
	v_cmp_eq_f32_e64 s[18:19], v73, v94
	v_cmp_lt_u32_e64 s[36:37], 29, v143
	s_and_b64 s[18:19], s[18:19], s[36:37]
	s_or_b64 s[12:13], s[12:13], s[18:19]
	v_cndmask_b32_e64 v130, 0, 1, s[12:13]
	v_cmp_lt_f32_e64 s[12:13], v73, v93
	v_cmp_eq_f32_e64 s[18:19], v73, v93
	v_cmp_eq_u32_e64 s[36:37], 31, v143
	s_and_b64 s[18:19], s[18:19], s[36:37]
	s_or_b64 s[12:13], s[12:13], s[18:19]
	v_cndmask_b32_e64 v94, 0, 1, s[12:13]
	v_add3_u32 v74, v74, v75, v77
	v_add3_u32 v74, v74, v76, v79
	v_add3_u32 v74, v74, v78, v81
	v_add3_u32 v74, v74, v80, v83
	v_add3_u32 v74, v74, v82, v85
	v_add3_u32 v74, v74, v84, v87
	v_add3_u32 v74, v74, v86, v89
	v_cmp_lt_f32_e64 s[12:13], v73, v90
	s_nop 1
	v_addc_co_u32_e64 v73, s[12:13], v74, v88, s[12:13]
	v_add_u32_e32 v73, v73, v92
	v_add3_u32 v73, v73, v91, v96
	v_add3_u32 v73, v73, v95, v132
	v_add3_u32 v73, v73, v131, v149
	v_add3_u32 v73, v73, v148, v153
	v_add3_u32 v73, v73, v152, v150
	v_add3_u32 v73, v73, v146, v133
	v_add3_u32 v73, v73, v130, v94
	v_cmp_gt_u32_e64 s[12:13], 16, v73
	s_and_b64 s[12:13], s[12:13], s[6:7]
	s_nop 0
	v_cndmask_b32_e64 v73, 0, 1, s[12:13]
	v_cmp_ne_u32_e64 s[12:13], 0, v73
	s_and_saveexec_b64 s[18:19], vcc
	s_nop 0
	v_mov_b32_e32 v73, s13
	v_mov_b32_e32 v74, s12
	v_add_u32_e32 v72, 0x24000, v72
	v_cndmask_b32_e64 v73, v73, v74, s[4:5]
	ds_write_b32 v72, v73
	s_or_b64 exec, exec, s[18:19]
	v_or_b32_e32 v70, 2, v70
	v_lshl_add_u32 v71, v70, 7, v71
	v_xor_b32_e32 v71, 8, v71
	v_xor_b32_e32 v68, 8, v68
	v_lshl_add_u32 v70, v70, 2, 0
	v_add_u32_e32 v95, 0x1c000, v70
	v_add_u32_e32 v96, 0x1c400, v70
	v_add_u32_e32 v97, 0x1c480, v70
	v_add_u32_e32 v130, 0x1c500, v70
	v_add_u32_e32 v131, 0x1c580, v70
	ds_read2st64_b32 v[72:73], v68 offset0:17 offset1:33
	ds_read2_b32 v[74:75], v69 offset0:34 offset1:66
	ds_read2st64_b32 v[76:77], v68 offset0:49 offset1:65
	ds_read2_b32 v[78:79], v69 offset0:98 offset1:130
	ds_read2st64_b32 v[80:81], v68 offset0:81 offset1:97
	ds_read2_b32 v[82:83], v69 offset0:162 offset1:194
	ds_read_b32 v71, v71
	ds_read_b32 v95, v95
	ds_read_b32 v96, v96
	ds_read_b32 v97, v97
	ds_read_b32 v130, v130
	ds_read_b32 v131, v131
	ds_read_b32 v68, v68 offset:28928
	ds_read_b32 v69, v69 offset:904
	v_add_u32_e32 v132, 0x1c600, v70
	v_add_u32_e32 v133, 0x1c680, v70
	v_add_u32_e32 v146, 0x1c700, v70
	v_add_u32_e32 v148, 0x1c780, v70
	ds_read_b32 v132, v132
	ds_read_b32 v133, v133
	ds_read_b32 v146, v146
	ds_read_b32 v148, v148
	v_or_b32_e32 v84, 4, v67
	v_or_b32_e32 v85, 8, v67
	v_or_b32_e32 v86, 12, v67
	v_or_b32_e32 v87, 16, v67
	v_or_b32_e32 v88, 20, v67
	v_or_b32_e32 v89, 24, v67
	v_or_b32_e32 v90, 28, v67
	v_or_b32_e32 v91, 32, v67
	v_or_b32_e32 v92, 36, v67
	v_or_b32_e32 v93, 40, v67
	v_or_b32_e32 v94, 44, v67
	v_or_b32_e32 v149, 48, v67
	v_or_b32_e32 v150, 52, v67
	v_or_b32_e32 v152, 56, v67
	v_or_b32_e32 v153, 60, v67
	s_waitcnt lgkmcnt(0)
	v_cndmask_b32_e64 v95, 0, v95, s[8:9]
	v_add_f32_e32 v71, v71, v95
	v_cndmask_b32_e64 v74, 0, v74, s[8:9]
	v_fma_f32 v71, v96, v71, 0
	v_add_f32_e32 v72, v72, v74
	v_fmac_f32_e32 v71, v97, v72
	v_cndmask_b32_e64 v72, 0, v75, s[8:9]
	v_add_f32_e32 v72, v73, v72
	v_fmac_f32_e32 v71, v130, v72
	v_cndmask_b32_e64 v72, 0, v78, s[8:9]
	v_add_f32_e32 v72, v76, v72
	v_fmac_f32_e32 v71, v131, v72
	v_cndmask_b32_e64 v72, 0, v79, s[8:9]
	v_add_f32_e32 v72, v77, v72
	v_fmac_f32_e32 v71, v132, v72
	v_cndmask_b32_e64 v72, 0, v82, s[8:9]
	v_add_f32_e32 v72, v80, v72
	v_fmac_f32_e32 v71, v133, v72
	v_cndmask_b32_e64 v72, 0, v83, s[8:9]
	v_add_f32_e32 v72, v81, v72
	v_cndmask_b32_e64 v69, 0, v69, s[8:9]
	v_fmac_f32_e32 v71, v146, v72
	v_add_f32_e32 v68, v68, v69
	v_fmac_f32_e32 v71, v148, v68
	v_cndmask_b32_e64 v68, v187, v71, s[6:7]
	v_cndmask_b32_e64 v68, v68, v188, s[10:11]
	ds_bpermute_b32 v73, v67, v68
	ds_bpermute_b32 v72, v84, v68
	ds_bpermute_b32 v75, v85, v68
	ds_bpermute_b32 v74, v86, v68
	ds_bpermute_b32 v77, v87, v68
	ds_bpermute_b32 v76, v88, v68
	ds_bpermute_b32 v79, v89, v68
	ds_bpermute_b32 v78, v90, v68
	ds_bpermute_b32 v81, v91, v68
	ds_bpermute_b32 v80, v92, v68
	ds_bpermute_b32 v83, v93, v68
	ds_bpermute_b32 v82, v94, v68
	ds_bpermute_b32 v85, v149, v68
	ds_bpermute_b32 v84, v150, v68
	ds_bpermute_b32 v87, v152, v68
	ds_bpermute_b32 v86, v153, v68
	s_waitcnt lgkmcnt(0)
	v_mov_b32_e32 v69, 1
	v_cmp_lt_f32_e64 s[8:9], v68, v73
	v_cmp_eq_f32_e64 s[10:11], v68, v73
	v_cmp_ne_u32_e64 s[12:13], 0, v143
	s_and_b64 s[10:11], s[10:11], s[12:13]
	s_or_b64 s[8:9], s[8:9], s[10:11]
	v_cndmask_b32_e64 v71, 0, 1, s[8:9]
	v_cmp_lt_f32_e64 s[8:9], v68, v72
	v_cmp_eq_f32_e64 s[10:11], v68, v72
	v_cmp_lt_u32_e64 s[12:13], 1, v143
	s_and_b64 s[10:11], s[10:11], s[12:13]
	s_or_b64 s[8:9], s[8:9], s[10:11]
	v_cndmask_b32_e64 v69, 0, 1, s[8:9]
	v_mov_b32_e32 v72, 1
	v_cmp_lt_f32_e64 s[8:9], v68, v75
	v_cmp_eq_f32_e64 s[10:11], v68, v75
	v_cmp_lt_u32_e64 s[12:13], 2, v143
	s_and_b64 s[10:11], s[10:11], s[12:13]
	s_or_b64 s[8:9], s[8:9], s[10:11]
	v_cndmask_b32_e64 v73, 0, 1, s[8:9]
	v_cmp_lt_f32_e64 s[8:9], v68, v74
	v_cmp_eq_f32_e64 s[10:11], v68, v74
	v_cmp_lt_u32_e64 s[12:13], 3, v143
	s_and_b64 s[10:11], s[10:11], s[12:13]
	s_or_b64 s[8:9], s[8:9], s[10:11]
	v_cndmask_b32_e64 v72, 0, 1, s[8:9]
	v_mov_b32_e32 v74, 1
	v_cmp_lt_f32_e64 s[8:9], v68, v77
	v_cmp_eq_f32_e64 s[10:11], v68, v77
	v_cmp_lt_u32_e64 s[12:13], 4, v143
	s_and_b64 s[10:11], s[10:11], s[12:13]
	s_or_b64 s[8:9], s[8:9], s[10:11]
	v_cndmask_b32_e64 v75, 0, 1, s[8:9]
	v_cmp_lt_f32_e64 s[8:9], v68, v76
	v_cmp_eq_f32_e64 s[10:11], v68, v76
	v_cmp_lt_u32_e64 s[12:13], 5, v143
	s_and_b64 s[10:11], s[10:11], s[12:13]
	s_or_b64 s[8:9], s[8:9], s[10:11]
	v_cndmask_b32_e64 v74, 0, 1, s[8:9]
	v_mov_b32_e32 v76, 1
	v_cmp_lt_f32_e64 s[8:9], v68, v79
	v_cmp_eq_f32_e64 s[10:11], v68, v79
	v_cmp_lt_u32_e64 s[12:13], 6, v143
	s_and_b64 s[10:11], s[10:11], s[12:13]
	s_or_b64 s[8:9], s[8:9], s[10:11]
	v_cndmask_b32_e64 v77, 0, 1, s[8:9]
	v_cmp_lt_f32_e64 s[8:9], v68, v78
	v_cmp_eq_f32_e64 s[10:11], v68, v78
	v_cmp_lt_u32_e64 s[12:13], 7, v143
	s_and_b64 s[10:11], s[10:11], s[12:13]
	s_or_b64 s[8:9], s[8:9], s[10:11]
	v_cndmask_b32_e64 v76, 0, 1, s[8:9]
	v_mov_b32_e32 v78, 1
	v_cmp_lt_f32_e64 s[8:9], v68, v81
	v_cmp_eq_f32_e64 s[10:11], v68, v81
	v_cmp_lt_u32_e64 s[12:13], 8, v143
	s_and_b64 s[10:11], s[10:11], s[12:13]
	s_or_b64 s[8:9], s[8:9], s[10:11]
	v_cndmask_b32_e64 v79, 0, 1, s[8:9]
	v_cmp_lt_f32_e64 s[8:9], v68, v80
	v_cmp_eq_f32_e64 s[10:11], v68, v80
	v_cmp_lt_u32_e64 s[12:13], 9, v143
	s_and_b64 s[10:11], s[10:11], s[12:13]
	s_or_b64 s[8:9], s[8:9], s[10:11]
	v_cndmask_b32_e64 v78, 0, 1, s[8:9]
	v_mov_b32_e32 v80, 1
	v_cmp_lt_f32_e64 s[8:9], v68, v83
	v_cmp_eq_f32_e64 s[10:11], v68, v83
	v_cmp_lt_u32_e64 s[12:13], 10, v143
	s_and_b64 s[10:11], s[10:11], s[12:13]
	s_or_b64 s[8:9], s[8:9], s[10:11]
	v_cndmask_b32_e64 v81, 0, 1, s[8:9]
	v_cmp_lt_f32_e64 s[8:9], v68, v82
	v_cmp_eq_f32_e64 s[10:11], v68, v82
	v_cmp_lt_u32_e64 s[12:13], 11, v143
	s_and_b64 s[10:11], s[10:11], s[12:13]
	s_or_b64 s[8:9], s[8:9], s[10:11]
	v_cndmask_b32_e64 v80, 0, 1, s[8:9]
	v_mov_b32_e32 v82, 1
	v_cmp_lt_f32_e64 s[8:9], v68, v85
	v_cmp_eq_f32_e64 s[10:11], v68, v85
	v_cmp_lt_u32_e64 s[12:13], 12, v143
	s_and_b64 s[10:11], s[10:11], s[12:13]
	s_or_b64 s[8:9], s[8:9], s[10:11]
	v_cndmask_b32_e64 v83, 0, 1, s[8:9]
	v_cmp_lt_f32_e64 s[8:9], v68, v84
	v_cmp_eq_f32_e64 s[10:11], v68, v84
	v_cmp_lt_u32_e64 s[12:13], 13, v143
	s_and_b64 s[10:11], s[10:11], s[12:13]
	s_or_b64 s[8:9], s[8:9], s[10:11]
	v_cndmask_b32_e64 v82, 0, 1, s[8:9]
	v_mov_b32_e32 v84, 1
	v_cmp_lt_f32_e64 s[8:9], v68, v87
	v_cmp_eq_f32_e64 s[10:11], v68, v87
	v_cmp_lt_u32_e64 s[12:13], 14, v143
	s_and_b64 s[10:11], s[10:11], s[12:13]
	s_or_b64 s[8:9], s[8:9], s[10:11]
	v_cndmask_b32_e64 v85, 0, 1, s[8:9]
	v_cmp_lt_f32_e64 s[8:9], v68, v86
	v_cmp_eq_f32_e64 s[10:11], v68, v86
	v_cmp_lt_u32_e64 s[12:13], 15, v143
	s_and_b64 s[10:11], s[10:11], s[12:13]
	s_or_b64 s[8:9], s[8:9], s[10:11]
	v_cndmask_b32_e64 v84, 0, 1, s[8:9]
	v_or_b32_e32 v86, 64, v67
	v_or_b32_e32 v87, 0x44, v67
	v_or_b32_e32 v88, 0x48, v67
	v_or_b32_e32 v89, 0x4c, v67
	v_or_b32_e32 v92, 0x50, v67
	v_or_b32_e32 v93, 0x54, v67
	v_or_b32_e32 v96, 0x58, v67
	v_or_b32_e32 v97, 0x5c, v67
	v_or_b32_e32 v132, 0x60, v67
	v_or_b32_e32 v148, 0x64, v67
	v_or_b32_e32 v149, 0x68, v67
	v_or_b32_e32 v150, 0x6c, v67
	v_or_b32_e32 v152, 0x70, v67
	v_or_b32_e32 v153, 0x74, v67
	v_or_b32_e32 v154, 0x78, v67
	v_or_b32_e32 v67, 0x7c, v67
	ds_bpermute_b32 v91, v86, v68
	ds_bpermute_b32 v90, v87, v68
	ds_bpermute_b32 v95, v88, v68
	ds_bpermute_b32 v94, v89, v68
	ds_bpermute_b32 v131, v92, v68
	ds_bpermute_b32 v130, v93, v68
	ds_bpermute_b32 v146, v96, v68
	ds_bpermute_b32 v133, v97, v68
	ds_bpermute_b32 v132, v132, v68
	ds_bpermute_b32 v97, v148, v68
	ds_bpermute_b32 v96, v149, v68
	ds_bpermute_b32 v93, v150, v68
	ds_bpermute_b32 v92, v152, v68
	ds_bpermute_b32 v89, v153, v68
	ds_bpermute_b32 v88, v154, v68
	ds_bpermute_b32 v67, v67, v68
	s_waitcnt lgkmcnt(0)
	v_mov_b32_e32 v86, 1
	v_cmp_lt_f32_e64 s[8:9], v68, v91
	v_cmp_eq_f32_e64 s[10:11], v68, v91
	v_cmp_lt_u32_e64 s[12:13], 16, v143
	s_and_b64 s[10:11], s[10:11], s[12:13]
	s_or_b64 s[8:9], s[8:9], s[10:11]
	v_cndmask_b32_e64 v87, 0, 1, s[8:9]
	v_cmp_lt_f32_e64 s[8:9], v68, v90
	v_cmp_eq_f32_e64 s[10:11], v68, v90
	v_cmp_lt_u32_e64 s[12:13], 17, v143
	s_and_b64 s[10:11], s[10:11], s[12:13]
	s_or_b64 s[8:9], s[8:9], s[10:11]
	v_cndmask_b32_e64 v86, 0, 1, s[8:9]
	v_mov_b32_e32 v90, 1
	v_cmp_lt_f32_e64 s[8:9], v68, v95
	v_cmp_eq_f32_e64 s[10:11], v68, v95
	v_cmp_lt_u32_e64 s[12:13], 18, v143
	s_and_b64 s[10:11], s[10:11], s[12:13]
	s_or_b64 s[8:9], s[8:9], s[10:11]
	v_cndmask_b32_e64 v91, 0, 1, s[8:9]
	v_cmp_lt_f32_e64 s[8:9], v68, v94
	v_cmp_eq_f32_e64 s[10:11], v68, v94
	v_cmp_lt_u32_e64 s[12:13], 19, v143
	s_and_b64 s[10:11], s[10:11], s[12:13]
	s_or_b64 s[8:9], s[8:9], s[10:11]
	v_cndmask_b32_e64 v90, 0, 1, s[8:9]
	v_mov_b32_e32 v94, 1
	v_cmp_lt_f32_e64 s[8:9], v68, v131
	v_cmp_eq_f32_e64 s[10:11], v68, v131
	v_cmp_lt_u32_e64 s[12:13], 20, v143
	s_and_b64 s[10:11], s[10:11], s[12:13]
	s_or_b64 s[8:9], s[8:9], s[10:11]
	v_cndmask_b32_e64 v95, 0, 1, s[8:9]
	v_cmp_lt_f32_e64 s[8:9], v68, v130
	v_cmp_eq_f32_e64 s[10:11], v68, v130
	v_cmp_lt_u32_e64 s[12:13], 21, v143
	s_and_b64 s[10:11], s[10:11], s[12:13]
	s_or_b64 s[8:9], s[8:9], s[10:11]
	v_cndmask_b32_e64 v94, 0, 1, s[8:9]
	v_mov_b32_e32 v130, 1
	v_cmp_lt_f32_e64 s[8:9], v68, v146
	v_cmp_eq_f32_e64 s[10:11], v68, v146
	v_cmp_lt_u32_e64 s[12:13], 22, v143
	s_and_b64 s[10:11], s[10:11], s[12:13]
	s_or_b64 s[8:9], s[8:9], s[10:11]
	v_cndmask_b32_e64 v131, 0, 1, s[8:9]
	v_cmp_lt_f32_e64 s[8:9], v68, v133
	v_cmp_eq_f32_e64 s[10:11], v68, v133
	v_cmp_lt_u32_e64 s[12:13], 23, v143
	s_and_b64 s[10:11], s[10:11], s[12:13]
	s_or_b64 s[8:9], s[8:9], s[10:11]
	v_cndmask_b32_e64 v130, 0, 1, s[8:9]
	v_mov_b32_e32 v133, 1
	v_cmp_lt_f32_e64 s[8:9], v68, v132
	v_cmp_eq_f32_e64 s[10:11], v68, v132
	v_cmp_lt_u32_e64 s[12:13], 24, v143
	s_and_b64 s[10:11], s[10:11], s[12:13]
	s_or_b64 s[8:9], s[8:9], s[10:11]
	v_cndmask_b32_e64 v146, 0, 1, s[8:9]
	v_cmp_lt_f32_e64 s[8:9], v68, v97
	v_cmp_eq_f32_e64 s[10:11], v68, v97
	v_cmp_lt_u32_e64 s[12:13], 25, v143
	s_and_b64 s[10:11], s[10:11], s[12:13]
	s_or_b64 s[8:9], s[8:9], s[10:11]
	v_cndmask_b32_e64 v133, 0, 1, s[8:9]
	v_mov_b32_e32 v97, 1
	v_cmp_lt_f32_e64 s[8:9], v68, v96
	v_cmp_eq_f32_e64 s[10:11], v68, v96
	v_cmp_lt_u32_e64 s[12:13], 26, v143
	s_and_b64 s[10:11], s[10:11], s[12:13]
	s_or_b64 s[8:9], s[8:9], s[10:11]
	v_cndmask_b32_e64 v132, 0, 1, s[8:9]
	v_cmp_lt_f32_e64 s[8:9], v68, v93
	v_cmp_eq_f32_e64 s[10:11], v68, v93
	v_cmp_lt_u32_e64 s[12:13], 27, v143
	s_and_b64 s[10:11], s[10:11], s[12:13]
	s_or_b64 s[8:9], s[8:9], s[10:11]
	v_cndmask_b32_e64 v97, 0, 1, s[8:9]
	v_mov_b32_e32 v93, 1
	v_cmp_lt_f32_e64 s[8:9], v68, v92
	v_cmp_eq_f32_e64 s[10:11], v68, v92
	v_cmp_lt_u32_e64 s[12:13], 28, v143
	s_and_b64 s[10:11], s[10:11], s[12:13]
	s_or_b64 s[8:9], s[8:9], s[10:11]
	v_cndmask_b32_e64 v96, 0, 1, s[8:9]
	v_cmp_lt_f32_e64 s[8:9], v68, v89
	v_cmp_eq_f32_e64 s[10:11], v68, v89
	v_cmp_lt_u32_e64 s[12:13], 29, v143
	s_and_b64 s[10:11], s[10:11], s[12:13]
	s_or_b64 s[8:9], s[8:9], s[10:11]
	v_cndmask_b32_e64 v93, 0, 1, s[8:9]
	v_cmp_lt_f32_e64 s[8:9], v68, v88
	v_cmp_eq_f32_e64 s[10:11], v68, v88
	v_cmp_eq_u32_e64 s[12:13], 31, v143
	s_and_b64 s[10:11], s[10:11], s[12:13]
	s_or_b64 s[8:9], s[8:9], s[10:11]
	v_cndmask_b32_e64 v89, 0, 1, s[8:9]
	v_add3_u32 v69, v69, v71, v73
	v_add3_u32 v69, v69, v72, v75
	v_add3_u32 v69, v69, v74, v77
	v_add3_u32 v69, v69, v76, v79
	v_add3_u32 v69, v69, v78, v81
	v_add3_u32 v69, v69, v80, v83
	v_add3_u32 v69, v69, v82, v85
	v_cmp_lt_f32_e64 s[8:9], v68, v67
	s_nop 1
	v_addc_co_u32_e64 v67, s[8:9], v69, v84, s[8:9]
	v_add_u32_e32 v67, v67, v87
	v_add3_u32 v67, v67, v86, v91
	v_add3_u32 v67, v67, v90, v95
	v_add3_u32 v67, v67, v94, v131
	v_add3_u32 v67, v67, v130, v146
	v_add3_u32 v67, v67, v133, v132
	v_add3_u32 v67, v67, v97, v96
	v_add3_u32 v67, v67, v93, v89
	v_cmp_gt_u32_e64 s[8:9], 16, v67
	s_and_b64 s[6:7], s[8:9], s[6:7]
	v_cndmask_b32_e64 v67, 0, 1, s[6:7]
	v_cmp_ne_u32_e64 s[6:7], 0, v67
	s_and_saveexec_b64 s[8:9], vcc
	s_nop 0
	v_mov_b32_e32 v68, s7
	v_mov_b32_e32 v69, s6
	v_add_u32_e32 v67, 0x24000, v70
	v_cndmask_b32_e64 v68, v68, v69, s[4:5]
	ds_write_b32 v67, v68
	s_or_b64 exec, exec, s[8:9]
